# attention inner loop: key distances carried as exact f32 per lane, mask = one unsigned compare of f32 bits, ALiBi via packed fma (56 VALU instead of 120 per iteration); on top of x2
# speedup vs baseline: 1.0272x; 1.0272x over previous
.LBB0_411:
	s_mul_hi_i32 s3, s16, 0x2aaaaaab
	s_lshr_b32 s12, s3, 31
	s_ashr_i32 s35, s3, 4
	s_add_i32 s35, s35, s12
	s_mul_i32 s3, s35, 0xffffffa0
	s_add_i32 s3, s3, s16
	s_and_b32 s40, s16, 31
	s_ashr_i32 s16, s3, 5
	s_lshl_b32 s34, s16, 1
	s_sub_i32 s12, 5, s34
	v_readfirstlane_b32 s2, v209
	s_lshr_b32 s3, 32, s34
	s_lshr_b32 s12, s40, s12
	s_mul_i32 s41, s12, s3
	s_ashr_i32 s3, s2, 2
	s_ashr_i32 s2, s2, 7
	s_and_b32 s33, s35, 7
	s_and_b32 s50, s3, -16
	s_max_i32 s42, s2, 4
	s_cmp_eq_u32 s40, s41
	s_cselect_b32 s51, s42, s2
	s_addk_i32 s3, 0x80
	s_ashr_i32 s42, s3, 5
	v_or_b32_e32 v114, s50, v189
	s_mov_b64 s[2:3], -1
	s_cmp_le_i32 s51, s42
	v_mbcnt_hi_u32_b32 v117, -1, v223
	s_cbranch_scc0 .LBB0_415
	s_add_i32 s3, s33, 1
	s_lshl_b32 s2, 1, s34
	v_cvt_f32_ubyte0_e32 v40, s3
	v_exp_f32_e64 v42, -v40
	v_cvt_f32_u32_e32 v43, s2
	v_mad_u64_u32 v[40:41], s[2:3], v114, s18, v[122:123]
	s_cmp_lt_i32 s51, s42
	s_cselect_b64 s[2:3], -1, 0
	s_cmp_lg_u64 s[2:3], 0
	s_addc_u32 s2, s51, 0
	s_lshr_b32 s3, s2, 2
	ds_read_b128 v[56:59], v40
	ds_read_b128 v[60:63], v40 offset:64
	v_mul_f32_e32 v40, v42, v43
	s_xor_b32 s3, s3, s17
	v_mbcnt_hi_u32_b32 v147, -1, v223
	v_mul_f32_e32 v129, 0x3fb8aa3b, v40
	s_lshl_b32 s3, s3, 7
	s_lshl_b32 s2, s2, 5
	v_and_b32_e32 v40, 64, v147
	s_and_b32 s3, s3, 0x80
	s_and_b32 s2, s2, 0x60
	v_xor_b32_e32 v145, 16, v147
	v_add_u32_e32 v146, 64, v40
	s_or_b32 s45, s3, s2
	s_lshr_b32 s2, s51, 2
	v_cmp_lt_i32_e32 vcc, v145, v146
	v_xor_b32_e32 v148, 32, v147
	s_xor_b32 s2, s2, s17
	v_cndmask_b32_e32 v40, v147, v145, vcc
	v_cmp_lt_i32_e32 vcc, v148, v146
	s_lshl_b32 s2, s2, 7
	s_lshl_b32 s43, s51, 5
	v_lshlrev_b32_e32 v150, 2, v40
	v_cndmask_b32_e32 v40, v147, v148, vcc
	s_and_b32 s2, s2, 0x80
	s_and_b32 s3, s43, 0x60
	v_lshlrev_b32_e32 v151, 2, v40
	v_add_u32_e32 v40, s50, v139
	v_mov_b32_e32 v97, 0
	s_or_b32 s44, s2, s3
	v_add_u32_e32 v149, 0x80, v114
	v_subrev_u32_e32 v152, s43, v40
	v_add_u32_e32 v177, 19, v152
	v_cvt_f32_i32_e32 v177, v177
	v_mov_b32_e32 v176, 0xc2800000
	s_mov_b32 s97, 0x43000001
	v_mov_b32_e32 v160, v177
	v_add_f32_e32 v161, -1.0, v177
	v_add_f32_e32 v162, -2.0, v177
	v_add_f32_e32 v163, 0xc0400000, v177
	v_add_f32_e32 v164, 0xc1800000, v177
	v_add_f32_e32 v165, 0xc1880000, v177
	v_add_f32_e32 v166, 0xc1900000, v177
	v_add_f32_e32 v167, 0xc1980000, v177
	v_add_f32_e32 v168, 0xc2000000, v177
	v_add_f32_e32 v169, 0xc2040000, v177
	v_add_f32_e32 v170, 0xc2080000, v177
	v_add_f32_e32 v171, 0xc20c0000, v177
	v_add_f32_e32 v172, 0xc2400000, v177
	v_add_f32_e32 v173, 0xc2440000, v177
	v_add_f32_e32 v174, 0xc2480000, v177
	v_add_f32_e32 v175, 0xc24c0000, v177
	v_mov_b32_e32 v96, 0xf149f2ca
	v_mov_b32_e32 v52, 0
	v_mov_b32_e32 v53, v97
	v_mov_b32_e32 v54, v97
	v_mov_b32_e32 v55, v97
	v_mov_b32_e32 v48, 0
	v_mov_b32_e32 v49, v97
	v_mov_b32_e32 v50, v97
	v_mov_b32_e32 v51, v97
	v_mov_b32_e32 v44, 0
	v_mov_b32_e32 v45, v97
	v_mov_b32_e32 v46, v97
	v_mov_b32_e32 v47, v97
	v_mov_b32_e32 v40, 0
	v_mov_b32_e32 v41, v97
	v_mov_b32_e32 v42, v97
	v_mov_b32_e32 v43, v97
.LBB0_413:
	v_bitop3_b32 v64, s45, v142, v189 bitop3:0x36
	v_bitop3_b32 v72, s45, v143, v189 bitop3:0x36
	v_bitop3_b32 v80, s44, v142, v189 bitop3:0x36
	v_bitop3_b32 v88, s44, v143, v189 bitop3:0x36
	v_mad_i32_i24 v68, v64, s18, v122
	v_mad_i32_i24 v76, v72, s18, v122
	v_mad_i32_i24 v84, v80, s18, v122
	v_mad_i32_i24 v92, v88, s18, v122
	ds_read_b128 v[64:67], v68 offset:18496
	ds_read_b128 v[68:71], v68 offset:18432
	ds_read_b128 v[72:75], v76 offset:18496
	ds_read_b128 v[76:79], v76 offset:18432
	ds_read_b128 v[80:83], v84 offset:18496
	ds_read_b128 v[84:87], v84 offset:18432
	ds_read_b128 v[88:91], v92 offset:18496
	ds_read_b128 v[92:95], v92 offset:18432
	s_waitcnt lgkmcnt(0)
	v_mfma_f32_16x16x32_bf16 v[92:95], v[92:95], v[56:59], 0
	v_cmp_gt_u32_e64 s[60:61], s97, v160
	v_cmp_gt_u32_e64 s[62:63], s97, v161
	v_cmp_gt_u32_e64 s[64:65], s97, v162
	v_cmp_gt_u32_e64 s[72:73], s97, v163
	v_mfma_f32_16x16x32_bf16 v[108:111], v[88:91], v[60:63], v[92:95]
	s_cmp_lt_i32 s51, s42
	s_cselect_b32 s101, s97, 0
	s_cselect_b64 s[2:3], -1, 0
	s_cmp_lg_u64 s[2:3], 0
	v_mfma_f32_16x16x32_bf16 v[84:87], v[84:87], v[56:59], 0
	s_addc_u32 s44, s51, 0
	v_mov_b32_e32 v153, v97
	v_mov_b32_e32 v154, v96
	v_cmp_gt_u32_e64 s[74:75], s97, v164
	v_cmp_gt_u32_e64 s[92:93], s97, v165
	v_cmp_gt_u32_e64 s[94:95], s97, v166
	v_cmp_gt_u32_e64 s[98:99], s97, v167
	s_lshl_b32 s52, s44, 5
	s_lshr_b32 s45, s51, 2
	v_pk_mul_f32 v[108:109], v[108:109], v[126:127] op_sel_hi:[1,0]
	v_pk_mul_f32 v[110:111], v[110:111], v[126:127] op_sel_hi:[1,0]
	v_pk_fma_f32 v[108:109], v[160:161], v[128:129], v[108:109] op_sel:[0,1,0] op_sel_hi:[1,1,1] neg_lo:[0,1,0] neg_hi:[0,1,0]
	v_pk_fma_f32 v[110:111], v[162:163], v[128:129], v[110:111] op_sel:[0,1,0] op_sel_hi:[1,1,1] neg_lo:[0,1,0] neg_hi:[0,1,0]
	v_mfma_f32_16x16x32_bf16 v[104:107], v[80:83], v[60:63], v[84:87]
	v_cndmask_b32_e64 v155, v144, v108, s[60:61]
	v_cndmask_b32_e64 v156, v144, v109, s[62:63]
	v_cndmask_b32_e64 v110, v144, v110, s[64:65]
	v_cndmask_b32_e64 v111, v144, v111, s[72:73]
	v_mfma_f32_16x16x32_bf16 v[76:79], v[76:79], v[56:59], 0
	v_max3_f32 v157, v155, s30, v156
	v_max3_f32 v157, v157, v110, v111
	v_pk_add_f32 v[160:161], v[160:161], v[176:177] op_sel_hi:[1,0]
	v_pk_add_f32 v[162:163], v[162:163], v[176:177] op_sel_hi:[1,0]
	v_cmp_gt_u32_e64 s[60:61], s101, v168
	v_cmp_gt_u32_e64 s[62:63], s101, v169
	v_cmp_gt_u32_e64 s[64:65], s101, v170
	v_cmp_gt_u32_e64 s[72:73], s101, v171
	s_xor_b32 s45, s45, s17
	s_lshl_b32 s45, s45, 7
	v_pk_mul_f32 v[104:105], v[104:105], v[126:127] op_sel_hi:[1,0]
	v_pk_mul_f32 v[106:107], v[106:107], v[126:127] op_sel_hi:[1,0]
	v_pk_fma_f32 v[104:105], v[164:165], v[128:129], v[104:105] op_sel:[0,1,0] op_sel_hi:[1,1,1] neg_lo:[0,1,0] neg_hi:[0,1,0]
	v_pk_fma_f32 v[106:107], v[166:167], v[128:129], v[106:107] op_sel:[0,1,0] op_sel_hi:[1,1,1] neg_lo:[0,1,0] neg_hi:[0,1,0]
	v_mfma_f32_16x16x32_bf16 v[100:103], v[72:75], v[60:63], v[76:79]
	v_cndmask_b32_e64 v108, v144, v104, s[74:75]
	v_cndmask_b32_e64 v109, v144, v105, s[92:93]
	v_cndmask_b32_e64 v106, v144, v106, s[94:95]
	v_cndmask_b32_e64 v107, v144, v107, s[98:99]
	v_mfma_f32_16x16x32_bf16 v[68:71], v[68:71], v[56:59], 0
	v_max3_f32 v157, v157, v108, v109
	v_max3_f32 v157, v157, v106, v107
	v_pk_add_f32 v[164:165], v[164:165], v[176:177] op_sel_hi:[1,0]
	v_pk_add_f32 v[166:167], v[166:167], v[176:177] op_sel_hi:[1,0]
	v_cmp_gt_u32_e64 s[74:75], s101, v172
	v_cmp_gt_u32_e64 s[92:93], s101, v173
	v_cmp_gt_u32_e64 s[94:95], s101, v174
	v_cmp_gt_u32_e64 s[98:99], s101, v175
	s_and_b32 s45, s45, 0x80
	s_and_b32 s50, s43, 0x60
	v_pk_mul_f32 v[100:101], v[100:101], v[126:127] op_sel_hi:[1,0]
	v_pk_mul_f32 v[102:103], v[102:103], v[126:127] op_sel_hi:[1,0]
	v_pk_fma_f32 v[100:101], v[168:169], v[128:129], v[100:101] op_sel:[0,1,0] op_sel_hi:[1,1,1] neg_lo:[0,1,0] neg_hi:[0,1,0]
	v_pk_fma_f32 v[102:103], v[170:171], v[128:129], v[102:103] op_sel:[0,1,0] op_sel_hi:[1,1,1] neg_lo:[0,1,0] neg_hi:[0,1,0]
	v_mfma_f32_16x16x32_bf16 v[96:99], v[64:67], v[60:63], v[68:71]
	v_cndmask_b32_e64 v104, v144, v100, s[60:61]
	v_cndmask_b32_e64 v105, v144, v101, s[62:63]
	v_cndmask_b32_e64 v102, v144, v102, s[64:65]
	v_cndmask_b32_e64 v103, v144, v103, s[72:73]
	v_max3_f32 v157, v157, v104, v105
	v_max3_f32 v157, v157, v102, v103
	v_pk_add_f32 v[168:169], v[168:169], v[176:177] op_sel_hi:[1,0]
	v_pk_add_f32 v[170:171], v[170:171], v[176:177] op_sel_hi:[1,0]
	s_or_b32 s45, s45, s50
	s_nop 1
	v_pk_mul_f32 v[96:97], v[96:97], v[126:127] op_sel_hi:[1,0]
	v_pk_mul_f32 v[98:99], v[98:99], v[126:127] op_sel_hi:[1,0]
	v_pk_fma_f32 v[96:97], v[172:173], v[128:129], v[96:97] op_sel:[0,1,0] op_sel_hi:[1,1,1] neg_lo:[0,1,0] neg_hi:[0,1,0]
	v_pk_fma_f32 v[98:99], v[174:175], v[128:129], v[98:99] op_sel:[0,1,0] op_sel_hi:[1,1,1] neg_lo:[0,1,0] neg_hi:[0,1,0]
	v_cndmask_b32_e64 v100, v144, v96, s[74:75]
	v_cndmask_b32_e64 v101, v144, v97, s[92:93]
	v_cndmask_b32_e64 v98, v144, v98, s[94:95]
	v_cndmask_b32_e64 v97, v144, v99, s[98:99]
	v_max3_f32 v157, v157, v100, v101
	v_max3_f32 v96, v157, v98, v97
	v_pk_add_f32 v[172:173], v[172:173], v[176:177] op_sel_hi:[1,0]
	v_pk_add_f32 v[174:175], v[174:175], v[176:177] op_sel_hi:[1,0]
	ds_bpermute_b32 v99, v150, v96
	s_lshr_b32 s50, s44, 2
	s_xor_b32 s50, s50, s17
	v_bitop3_b32 v64, s45, v123, v143 bitop3:0xde
	s_lshl_b32 s50, s50, 7
	s_waitcnt lgkmcnt(0)
	v_max_f32_e32 v99, v99, v99
	v_max_f32_e32 v96, v96, v99
	ds_bpermute_b32 v99, v151, v96
	v_mad_u32_u24 v76, v64, s18, 0
	v_bitop3_b32 v64, s45, v130, v143 bitop3:0xde
	s_and_b32 s50, s50, 0x80
	s_and_b32 s44, s52, 0x60
	s_waitcnt lgkmcnt(0)
	v_max3_f32 v96, v154, v96, v99
	v_sub_f32_e32 v127, v155, v96
	v_exp_f32_e32 v127, v127
	v_sub_f32_e32 v128, v156, v96
	v_exp_f32_e32 v128, v128
	v_sub_f32_e32 v110, v110, v96
	v_mad_u32_u24 v78, v64, s18, 0
	v_exp_f32_e32 v110, v110
	v_sub_f32_e32 v111, v111, v96
	s_or_b32 s44, s50, s44
	v_add_u32_e32 v72, v76, v125
	v_add_u32_e32 v74, v78, v125
	v_add_u32_e32 v76, v76, v131
	v_add_u32_e32 v78, v78, v131
	v_exp_f32_e32 v111, v111
	v_sub_f32_e32 v108, v108, v96
	v_sub_f32_e32 v97, v97, v96
	ds_read_b64_tr_b16 v[70:71], v74 offset:55296
	ds_read_b64_tr_b16 v[66:67], v74 offset:55328
	ds_read_b64_tr_b16 v[68:69], v72 offset:55296
	ds_read_b64_tr_b16 v[64:65], v72 offset:55328
	ds_read_b64_tr_b16 v[72:73], v72 offset:55360
	ds_read_b64_tr_b16 v[74:75], v74 offset:55360
	ds_read_b64_tr_b16 v[76:77], v76 offset:55296
	ds_read_b64_tr_b16 v[78:79], v78 offset:55296
	v_bitop3_b32 v80, s44, v123, v143 bitop3:0xde
	v_exp_f32_e32 v108, v108
	v_sub_f32_e32 v109, v109, v96
	v_exp_f32_e32 v158, v97
	v_add_f32_e32 v97, 0, v127
	v_mad_u32_u24 v92, v80, s18, 0
	v_bitop3_b32 v80, s44, v130, v143 bitop3:0xde
	v_exp_f32_e32 v109, v109
	v_sub_f32_e32 v106, v106, v96
	v_add_f32_e32 v97, v128, v97
	v_mad_u32_u24 v94, v80, s18, 0
	v_exp_f32_e32 v106, v106
	v_sub_f32_e32 v107, v107, v96
	v_sub_f32_e32 v102, v102, v96
	v_add_f32_e32 v97, v110, v97
	v_add_u32_e32 v88, v92, v125
	v_add_u32_e32 v90, v94, v125
	v_add_u32_e32 v92, v92, v131
	v_add_u32_e32 v94, v94, v131
	v_sub_f32_e32 v99, v154, v96
	v_exp_f32_e32 v107, v107
	v_sub_f32_e32 v104, v104, v96
	v_exp_f32_e32 v154, v102
	v_sub_f32_e32 v102, v103, v96
	v_add_f32_e32 v97, v111, v97
	ds_read_b64_tr_b16 v[86:87], v90 offset:55296
	ds_read_b64_tr_b16 v[82:83], v90 offset:55328
	ds_read_b64_tr_b16 v[84:85], v88 offset:55296
	ds_read_b64_tr_b16 v[80:81], v88 offset:55328
	ds_read_b64_tr_b16 v[88:89], v88 offset:55360
	ds_read_b64_tr_b16 v[90:91], v90 offset:55360
	ds_read_b64_tr_b16 v[92:93], v92 offset:55296
	ds_read_b64_tr_b16 v[94:95], v94 offset:55296
	v_exp_f32_e32 v104, v104
	v_sub_f32_e32 v105, v105, v96
	v_exp_f32_e32 v103, v102
	v_exp_f32_e32 v102, v99
	v_add_f32_e32 v97, v108, v97
	s_add_i32 s50, s51, 2
	v_exp_f32_e32 v105, v105
	v_add_f32_e32 v97, v109, v97
	s_min_i32 s44, s50, s42
	v_sub_f32_e32 v100, v100, v96
	v_add_f32_e32 v97, v106, v97
	s_add_i32 s45, s51, 3
	s_lshr_b32 s51, s44, 2
	v_exp_f32_e32 v155, v100
	v_sub_f32_e32 v100, v101, v96
	v_sub_f32_e32 v98, v98, v96
	v_add_f32_e32 v97, v107, v97
	s_xor_b32 s51, s51, s17
	v_exp_f32_e32 v156, v100
	v_exp_f32_e32 v157, v98
	v_pk_mul_f32 v[54:55], v[54:55], v[102:103] op_sel_hi:[1,0]
	v_pk_mul_f32 v[52:53], v[52:53], v[102:103] op_sel_hi:[1,0]
	v_pk_mul_f32 v[50:51], v[50:51], v[102:103] op_sel_hi:[1,0]
	v_pk_mul_f32 v[48:49], v[48:49], v[102:103] op_sel_hi:[1,0]
	v_pk_mul_f32 v[46:47], v[46:47], v[102:103] op_sel_hi:[1,0]
	v_pk_mul_f32 v[44:45], v[44:45], v[102:103] op_sel_hi:[1,0]
	v_pk_mul_f32 v[42:43], v[42:43], v[102:103] op_sel_hi:[1,0]
	v_pk_mul_f32 v[40:41], v[40:41], v[102:103] op_sel_hi:[1,0]
	v_add_f32_e32 v97, v104, v97
	v_cvt_pk_bf16_f32 v98, v127, v128
	v_cvt_pk_bf16_f32 v99, v110, v111
	v_cvt_pk_bf16_f32 v100, v108, v109
	v_cvt_pk_bf16_f32 v101, v106, v107
	s_lshl_b32 s51, s51, 7
	s_lshl_b32 s44, s44, 5
	v_add_f32_e32 v97, v105, v97
	s_waitcnt lgkmcnt(13)
	v_mfma_f32_16x16x32_bf16 v[52:55], v[68:71], v[98:101], v[52:55]
	s_min_i32 s45, s45, s42
	s_and_b32 s51, s51, 0x80
	s_and_b32 s44, s44, 0x60
	s_waitcnt lgkmcnt(12)
	v_mfma_f32_16x16x32_bf16 v[48:51], v[64:67], v[98:101], v[48:51]
	v_add_f32_e32 v97, v154, v97
	s_or_b32 s44, s51, s44
	s_lshr_b32 s51, s45, 2
	s_waitcnt lgkmcnt(10)
	v_mfma_f32_16x16x32_bf16 v[44:47], v[72:75], v[98:101], v[44:47]
	v_add_f32_e32 v97, v103, v97
	s_xor_b32 s51, s51, s17
	v_add_f32_e32 v97, v155, v97
	s_waitcnt lgkmcnt(8)
	v_mfma_f32_16x16x32_bf16 v[40:43], v[76:79], v[98:101], v[40:43]
	v_cvt_pk_bf16_f32 v64, v104, v105
	v_cvt_pk_bf16_f32 v65, v154, v103
	v_cvt_pk_bf16_f32 v66, v155, v156
	v_cvt_pk_bf16_f32 v67, v157, v158
	s_lshl_b32 s51, s51, 7
	s_lshl_b32 s45, s45, 5
	v_add_f32_e32 v97, v156, v97
	s_waitcnt lgkmcnt(5)
	v_mfma_f32_16x16x32_bf16 v[52:55], v[84:87], v[64:67], v[52:55]
	s_and_b32 s51, s51, 0x80
	s_and_b32 s45, s45, 0x60
	v_add_f32_e32 v97, v157, v97
	s_waitcnt lgkmcnt(4)
	v_mfma_f32_16x16x32_bf16 v[48:51], v[80:83], v[64:67], v[48:51]
	s_or_b32 s45, s51, s45
	v_add_f32_e32 v97, v158, v97
	s_add_i32 s43, s43, 64
	s_waitcnt lgkmcnt(2)
	v_mfma_f32_16x16x32_bf16 v[44:47], v[88:91], v[64:67], v[44:47]
	v_fmac_f32_e32 v97, v153, v102
	v_subrev_u32_e32 v152, 64, v152
	s_cmp_gt_i32 s50, s42
	s_waitcnt lgkmcnt(0)
	v_mfma_f32_16x16x32_bf16 v[40:43], v[92:95], v[64:67], v[40:43]
	s_mov_b32 s51, s50
	s_cbranch_scc0 .LBB0_413
	s_mov_b64 s[2:3], 0
